# speedup vs baseline: 1.0742x; 1.0054x over previous
; template <int NS, bool LN, bool WF32, bool WBF, int SKMODE>
; DI_ void row_pass(const float* Xin, float* Xout, bf16_t* XBo, const float* g, const float* b, const float* WsT, float* sk_out, const float* sk_bias, int row0, int nrows, int gw, int NGW, int lane) {
;     ...
;     if (row0 + gw < row0 + nrows) { const f32x4* xr = (const f32x4*)(Xin + (size_t)(row0 + gw) * D) + lane;
; #pragma unroll
;         for (int j = 0; j < 4; ++j) nv[j] = xr[64 * j]; }
;     for (int row = row0 + gw; row < row0 + nrows; row += NGW) {
;         f32x4 v[4];
; #pragma unroll
;         for (int j = 0; j < 4; ++j) v[j] = nv[j];
;         if (row + NGW < row0 + nrows) { const f32x4* xr = (const f32x4*)(Xin + (size_t)(row + NGW) * D) + lane;
; #pragma unroll
;             for (int j = 0; j < 4; ++j) nv[j] = xr[64 * j]; }
;         if (LN) {
;             float s = 0.f;
; #pragma unroll
;             for (int j = 0; j < 4; ++j) s += (v[j][0] + v[j][1]) + (v[j][2] + v[j][3]);
;             const float mean = wave_sum(s) * (1.f / D); float s2 = 0.f;
; #pragma unroll
;             for (int j = 0; j < 4; ++j) { v[j] = v[j] - mean; s2 += (v[j][0] * v[j][0] + v[j][1] * v[j][1]) + (v[j][2] * v[j][2] + v[j][3] * v[j][3]); }
;             const float rstd = 1.f / sqrtf(wave_sum(s2) * (1.f / D) + LN_EPS);
; #pragma unroll
;             for (int j = 0; j < 4; ++j) { const f32x4 gg = ((const f32x4*)g)[lane + 64 * j], bb = ((const f32x4*)b)[lane + 64 * j]; v[j] = v[j] * rstd * gg + bb; }
;         }
;         if (WF32) {
;             f32x4* xo = (f32x4*)(Xout + (size_t)row * D) + lane;
; #pragma unroll
;             for (int j = 0; j < 4; ++j) xo[64 * j] = v[j];
;         }
;         if (WBF) {
;             u32x2* xo = (u32x2*)(XBo + (size_t)row * D) + lane;
; #pragma unroll
;             for (int j = 0; j < 4; ++j) { u32x2 w; w.x = pk2(v[j][0], v[j][1]); w.y = pk2(v[j][2], v[j][3]); xo[64 * j] = w; }
;         }
;         if (NS > 0) {
; #pragma unroll 1
;             for (int grp = 0; grp < NS / 8; ++grp) {
;                 float a[8];
; #pragma unroll
;                 for (int jc = 0; jc < 8; ++jc) {
;                     float s = 0.f;
; #pragma unroll
;                     for (int j = 0; j < 4; ++j) { const f32x4 w = *(const f32x4*)(WsT + (8 * grp + jc) * WST + 4 * (lane + 64 * j)); s += (v[j][0] * w[0] + v[j][1] * w[1]) + (v[j][2] * w[2] + v[j][3] * w[3]); }
.LBB0_40:
	s_or_b64 exec, exec, s[0:1]
	v_mov_b32_e32 v18, v187
	s_add_u32 s86, s90, 0x4000000
	s_waitcnt lgkmcnt(0)
	s_barrier
	s_addc_u32 s87, s91, 0
	v_readfirstlane_b32 s0, v18
	s_ashr_i32 s0, s0, 6
	s_add_i32 s20, s0, s95
	s_add_u32 s3, s90, 0x14500000
	s_addc_u32 s33, s91, 0
	s_cmpk_gt_i32 s20, 0x7fff
	v_mbcnt_lo_u32_b32 v149, -1, 0
	s_cbranch_scc1 .LBB0_50
	s_lshl_b32 s0, s20, 4
	v_and_b32_e32 v1, 63, v18
	v_and_b32_e32 v2, 15, v1
	v_lshrrev_b32_e32 v3, 4, v1
	v_add_u32_e32 v4, s0, v2
	v_lshlrev_b32_e32 v6, 12, v4
	v_lshl_add_u32 v6, v3, 5, v6
	v_mov_b32_e32 v7, 0
	v_lshl_add_u64 v[6:7], s[56:57], 0, v[6:7]
	v_lshlrev_b32_e32 v8, 11, v4
	v_lshl_add_u32 v8, v3, 4, v8
	v_mov_b32_e32 v9, 0
	v_lshl_add_u64 v[8:9], s[86:87], 0, v[8:9]
	v_mul_u32_u24_e32 v10, 0x1010, v2
	v_lshl_add_u32 v10, v3, 5, v10
	v_lshlrev_b32_e32 v11, 2, v2
	v_mov_b32_e32 v12, 0
	v_mov_b32_e32 v13, 0
	v_mov_b32_e32 v14, 0
	v_mov_b32_e32 v15, 0
	v_mov_b32_e32 v16, 0
	v_mov_b32_e32 v17, 0
	v_mov_b32_e32 v18, 0
	v_mov_b32_e32 v19, 0
	global_load_dwordx4 v[98:101], v[6:7], off
	global_load_dwordx4 v[102:105], v[6:7], off offset:16
	global_load_dwordx4 v[106:109], v[6:7], off offset:128
	global_load_dwordx4 v[110:113], v[6:7], off offset:144
	global_load_dwordx4 v[114:117], v[6:7], off offset:256
	global_load_dwordx4 v[118:121], v[6:7], off offset:272
	global_load_dwordx4 v[122:125], v[6:7], off offset:384
	global_load_dwordx4 v[126:129], v[6:7], off offset:400
	global_load_dwordx4 v[130:133], v[6:7], off offset:512
	global_load_dwordx4 v[134:137], v[6:7], off offset:528
	global_load_dwordx4 v[138:141], v[6:7], off offset:640
	global_load_dwordx4 v[142:145], v[6:7], off offset:656
	ds_read_b128 v[20:23], v10
	ds_read_b128 v[24:27], v10 offset:16
	ds_read_b128 v[28:31], v10 offset:128
	ds_read_b128 v[32:35], v10 offset:144
	global_load_dwordx4 v[150:153], v[6:7], off offset:768
	global_load_dwordx4 v[154:157], v[6:7], off offset:784
	global_load_dwordx4 v[158:161], v[6:7], off offset:896
	global_load_dwordx4 v[162:165], v[6:7], off offset:912
	ds_read_b128 v[36:39], v10 offset:256
	ds_read_b128 v[40:43], v10 offset:272
	ds_read_b128 v[44:47], v10 offset:384
	ds_read_b128 v[48:51], v10 offset:400
	s_waitcnt vmcnt(12)
	s_waitcnt lgkmcnt(4)
	v_mfma_f32_16x16x4_f32 v[12:15], v98, v20, v[12:15]
	v_mfma_f32_16x16x4_f32 v[16:19], v99, v21, v[16:19]
	v_cvt_pk_bf16_f32 v52, v98, v99
	v_mfma_f32_16x16x4_f32 v[12:15], v100, v22, v[12:15]
	v_mfma_f32_16x16x4_f32 v[16:19], v101, v23, v[16:19]
	v_cvt_pk_bf16_f32 v53, v100, v101
	v_mfma_f32_16x16x4_f32 v[12:15], v102, v24, v[12:15]
	v_mfma_f32_16x16x4_f32 v[16:19], v103, v25, v[16:19]
	v_cvt_pk_bf16_f32 v54, v102, v103
	v_mfma_f32_16x16x4_f32 v[12:15], v104, v26, v[12:15]
	v_mfma_f32_16x16x4_f32 v[16:19], v105, v27, v[16:19]
	v_cvt_pk_bf16_f32 v55, v104, v105
	v_mfma_f32_16x16x4_f32 v[12:15], v106, v28, v[12:15]
	v_mfma_f32_16x16x4_f32 v[16:19], v107, v29, v[16:19]
	v_cvt_pk_bf16_f32 v56, v106, v107
	v_mfma_f32_16x16x4_f32 v[12:15], v108, v30, v[12:15]
	v_mfma_f32_16x16x4_f32 v[16:19], v109, v31, v[16:19]
	v_cvt_pk_bf16_f32 v57, v108, v109
	v_mfma_f32_16x16x4_f32 v[12:15], v110, v32, v[12:15]
	v_mfma_f32_16x16x4_f32 v[16:19], v111, v33, v[16:19]
	v_cvt_pk_bf16_f32 v58, v110, v111
	v_mfma_f32_16x16x4_f32 v[12:15], v112, v34, v[12:15]
	v_mfma_f32_16x16x4_f32 v[16:19], v113, v35, v[16:19]
	v_cvt_pk_bf16_f32 v59, v112, v113
	global_store_dwordx4 v[8:9], v[52:55], off
	global_store_dwordx4 v[8:9], v[56:59], off offset:64
	global_load_dwordx4 v[98:101], v[6:7], off offset:1024
	global_load_dwordx4 v[102:105], v[6:7], off offset:1040
	global_load_dwordx4 v[106:109], v[6:7], off offset:1152
	global_load_dwordx4 v[110:113], v[6:7], off offset:1168
	ds_read_b128 v[20:23], v10 offset:512
	ds_read_b128 v[24:27], v10 offset:528
	ds_read_b128 v[28:31], v10 offset:640
	ds_read_b128 v[32:35], v10 offset:656
	s_waitcnt vmcnt(14)
	s_waitcnt lgkmcnt(4)
	v_mfma_f32_16x16x4_f32 v[12:15], v114, v36, v[12:15]
	v_mfma_f32_16x16x4_f32 v[16:19], v115, v37, v[16:19]
	v_cvt_pk_bf16_f32 v60, v114, v115
	v_mfma_f32_16x16x4_f32 v[12:15], v116, v38, v[12:15]
	v_mfma_f32_16x16x4_f32 v[16:19], v117, v39, v[16:19]
	v_cvt_pk_bf16_f32 v61, v116, v117
	v_mfma_f32_16x16x4_f32 v[12:15], v118, v40, v[12:15]
	v_mfma_f32_16x16x4_f32 v[16:19], v119, v41, v[16:19]
	v_cvt_pk_bf16_f32 v62, v118, v119
	v_mfma_f32_16x16x4_f32 v[12:15], v120, v42, v[12:15]
	v_mfma_f32_16x16x4_f32 v[16:19], v121, v43, v[16:19]
	v_cvt_pk_bf16_f32 v63, v120, v121
	v_mfma_f32_16x16x4_f32 v[12:15], v122, v44, v[12:15]
	v_mfma_f32_16x16x4_f32 v[16:19], v123, v45, v[16:19]
	v_cvt_pk_bf16_f32 v64, v122, v123
	v_mfma_f32_16x16x4_f32 v[12:15], v124, v46, v[12:15]
	v_mfma_f32_16x16x4_f32 v[16:19], v125, v47, v[16:19]
	v_cvt_pk_bf16_f32 v65, v124, v125
	v_mfma_f32_16x16x4_f32 v[12:15], v126, v48, v[12:15]
	v_mfma_f32_16x16x4_f32 v[16:19], v127, v49, v[16:19]
	v_cvt_pk_bf16_f32 v66, v126, v127
	v_mfma_f32_16x16x4_f32 v[12:15], v128, v50, v[12:15]
	v_mfma_f32_16x16x4_f32 v[16:19], v129, v51, v[16:19]
	v_cvt_pk_bf16_f32 v67, v128, v129
	global_store_dwordx4 v[8:9], v[60:63], off offset:128
	global_store_dwordx4 v[8:9], v[64:67], off offset:192
	global_load_dwordx4 v[114:117], v[6:7], off offset:1280
	global_load_dwordx4 v[118:121], v[6:7], off offset:1296
	global_load_dwordx4 v[122:125], v[6:7], off offset:1408
	global_load_dwordx4 v[126:129], v[6:7], off offset:1424
	ds_read_b128 v[36:39], v10 offset:768
	ds_read_b128 v[40:43], v10 offset:784
	ds_read_b128 v[44:47], v10 offset:896
	ds_read_b128 v[48:51], v10 offset:912
	s_waitcnt vmcnt(16)
	s_waitcnt lgkmcnt(4)
; DI_ unsigned pk2(float lo, float hi) { typedef float f2 __attribute__((ext_vector_type(2))); typedef __bf16 b2 __attribute__((ext_vector_type(2))); f2 v = {lo, hi}; b2 b = __builtin_convertvector(v, b2); return __builtin_bit_cast(unsigned, b); }
; template <int NS, bool LN, bool WF32, bool WBF, int SKMODE>
; DI_ void row_pass(const float* Xin, float* Xout, bf16_t* XBo, const float* g, const float* b, const float* WsT, float* sk_out, const float* sk_bias, int row0, int nrows, int gw, int NGW, int lane) {
;     ...
;         if (WBF) {
;             u32x2* xo = (u32x2*)(XBo + (size_t)row * D) + lane;
; #pragma unroll
;             for (int j = 0; j < 4; ++j) { u32x2 w; w.x = pk2(v[j][0], v[j][1]); w.y = pk2(v[j][2], v[j][3]); xo[64 * j] = w; }
;         }
;         if (NS > 0) {
; #pragma unroll 1
;             for (int grp = 0; grp < NS / 8; ++grp) {
;                 float a[8];
; #pragma unroll
;                 for (int jc = 0; jc < 8; ++jc) {
;                     float s = 0.f;
; #pragma unroll
;                     for (int j = 0; j < 4; ++j) { const f32x4 w = *(const f32x4*)(WsT + (8 * grp + jc) * WST + 4 * (lane + 64 * j)); s += (v[j][0] * w[0] + v[j][1] * w[1]) + (v[j][2] * w[2] + v[j][3] * w[3]); }
	v_mfma_f32_16x16x4_f32 v[12:15], v130, v20, v[12:15]
	v_mfma_f32_16x16x4_f32 v[16:19], v131, v21, v[16:19]
	v_cvt_pk_bf16_f32 v52, v130, v131
	v_mfma_f32_16x16x4_f32 v[12:15], v132, v22, v[12:15]
	v_mfma_f32_16x16x4_f32 v[16:19], v133, v23, v[16:19]
	v_cvt_pk_bf16_f32 v53, v132, v133
	v_mfma_f32_16x16x4_f32 v[12:15], v134, v24, v[12:15]
	v_mfma_f32_16x16x4_f32 v[16:19], v135, v25, v[16:19]
	v_cvt_pk_bf16_f32 v54, v134, v135
	v_mfma_f32_16x16x4_f32 v[12:15], v136, v26, v[12:15]
	v_mfma_f32_16x16x4_f32 v[16:19], v137, v27, v[16:19]
	v_cvt_pk_bf16_f32 v55, v136, v137
	v_mfma_f32_16x16x4_f32 v[12:15], v138, v28, v[12:15]
	v_mfma_f32_16x16x4_f32 v[16:19], v139, v29, v[16:19]
	v_cvt_pk_bf16_f32 v56, v138, v139
	v_mfma_f32_16x16x4_f32 v[12:15], v140, v30, v[12:15]
	v_mfma_f32_16x16x4_f32 v[16:19], v141, v31, v[16:19]
	v_cvt_pk_bf16_f32 v57, v140, v141
	v_mfma_f32_16x16x4_f32 v[12:15], v142, v32, v[12:15]
	v_mfma_f32_16x16x4_f32 v[16:19], v143, v33, v[16:19]
	v_cvt_pk_bf16_f32 v58, v142, v143
	v_mfma_f32_16x16x4_f32 v[12:15], v144, v34, v[12:15]
	v_mfma_f32_16x16x4_f32 v[16:19], v145, v35, v[16:19]
	v_cvt_pk_bf16_f32 v59, v144, v145
	global_store_dwordx4 v[8:9], v[52:55], off offset:256
	global_store_dwordx4 v[8:9], v[56:59], off offset:320
	global_load_dwordx4 v[130:133], v[6:7], off offset:1536
	global_load_dwordx4 v[134:137], v[6:7], off offset:1552
	global_load_dwordx4 v[138:141], v[6:7], off offset:1664
	global_load_dwordx4 v[142:145], v[6:7], off offset:1680
	ds_read_b128 v[20:23], v10 offset:1024
	ds_read_b128 v[24:27], v10 offset:1040
	ds_read_b128 v[28:31], v10 offset:1152
	ds_read_b128 v[32:35], v10 offset:1168
	s_waitcnt vmcnt(18)
	s_waitcnt lgkmcnt(4)
	v_mfma_f32_16x16x4_f32 v[12:15], v150, v36, v[12:15]
	v_mfma_f32_16x16x4_f32 v[16:19], v151, v37, v[16:19]
	v_cvt_pk_bf16_f32 v60, v150, v151
	v_mfma_f32_16x16x4_f32 v[12:15], v152, v38, v[12:15]
	v_mfma_f32_16x16x4_f32 v[16:19], v153, v39, v[16:19]
	v_cvt_pk_bf16_f32 v61, v152, v153
	v_mfma_f32_16x16x4_f32 v[12:15], v154, v40, v[12:15]
	v_mfma_f32_16x16x4_f32 v[16:19], v155, v41, v[16:19]
	v_cvt_pk_bf16_f32 v62, v154, v155
	v_mfma_f32_16x16x4_f32 v[12:15], v156, v42, v[12:15]
	v_mfma_f32_16x16x4_f32 v[16:19], v157, v43, v[16:19]
	v_cvt_pk_bf16_f32 v63, v156, v157
	v_mfma_f32_16x16x4_f32 v[12:15], v158, v44, v[12:15]
	v_mfma_f32_16x16x4_f32 v[16:19], v159, v45, v[16:19]
	v_cvt_pk_bf16_f32 v64, v158, v159
	v_mfma_f32_16x16x4_f32 v[12:15], v160, v46, v[12:15]
	v_mfma_f32_16x16x4_f32 v[16:19], v161, v47, v[16:19]
	v_cvt_pk_bf16_f32 v65, v160, v161
	v_mfma_f32_16x16x4_f32 v[12:15], v162, v48, v[12:15]
	v_mfma_f32_16x16x4_f32 v[16:19], v163, v49, v[16:19]
	v_cvt_pk_bf16_f32 v66, v162, v163
	v_mfma_f32_16x16x4_f32 v[12:15], v164, v50, v[12:15]
	v_mfma_f32_16x16x4_f32 v[16:19], v165, v51, v[16:19]
	v_cvt_pk_bf16_f32 v67, v164, v165
	global_store_dwordx4 v[8:9], v[60:63], off offset:384
	global_store_dwordx4 v[8:9], v[64:67], off offset:448
	global_load_dwordx4 v[150:153], v[6:7], off offset:1792
	global_load_dwordx4 v[154:157], v[6:7], off offset:1808
	global_load_dwordx4 v[158:161], v[6:7], off offset:1920
	global_load_dwordx4 v[162:165], v[6:7], off offset:1936
	ds_read_b128 v[36:39], v10 offset:1280
	ds_read_b128 v[40:43], v10 offset:1296
	ds_read_b128 v[44:47], v10 offset:1408
	ds_read_b128 v[48:51], v10 offset:1424
	s_waitcnt vmcnt(18)
	s_waitcnt lgkmcnt(4)
	v_mfma_f32_16x16x4_f32 v[12:15], v98, v20, v[12:15]
	v_mfma_f32_16x16x4_f32 v[16:19], v99, v21, v[16:19]
	v_cvt_pk_bf16_f32 v52, v98, v99
	v_mfma_f32_16x16x4_f32 v[12:15], v100, v22, v[12:15]
	v_mfma_f32_16x16x4_f32 v[16:19], v101, v23, v[16:19]
	v_cvt_pk_bf16_f32 v53, v100, v101
	v_mfma_f32_16x16x4_f32 v[12:15], v102, v24, v[12:15]
	v_mfma_f32_16x16x4_f32 v[16:19], v103, v25, v[16:19]
	v_cvt_pk_bf16_f32 v54, v102, v103
	v_mfma_f32_16x16x4_f32 v[12:15], v104, v26, v[12:15]
	v_mfma_f32_16x16x4_f32 v[16:19], v105, v27, v[16:19]
	v_cvt_pk_bf16_f32 v55, v104, v105
	v_mfma_f32_16x16x4_f32 v[12:15], v106, v28, v[12:15]
	v_mfma_f32_16x16x4_f32 v[16:19], v107, v29, v[16:19]
	v_cvt_pk_bf16_f32 v56, v106, v107
	v_mfma_f32_16x16x4_f32 v[12:15], v108, v30, v[12:15]
	v_mfma_f32_16x16x4_f32 v[16:19], v109, v31, v[16:19]
	v_cvt_pk_bf16_f32 v57, v108, v109
	v_mfma_f32_16x16x4_f32 v[12:15], v110, v32, v[12:15]
	v_mfma_f32_16x16x4_f32 v[16:19], v111, v33, v[16:19]
	v_cvt_pk_bf16_f32 v58, v110, v111
	v_mfma_f32_16x16x4_f32 v[12:15], v112, v34, v[12:15]
	v_mfma_f32_16x16x4_f32 v[16:19], v113, v35, v[16:19]
	v_cvt_pk_bf16_f32 v59, v112, v113
	global_store_dwordx4 v[8:9], v[52:55], off offset:512
	global_store_dwordx4 v[8:9], v[56:59], off offset:576
	global_load_dwordx4 v[98:101], v[6:7], off offset:2048
	global_load_dwordx4 v[102:105], v[6:7], off offset:2064
	global_load_dwordx4 v[106:109], v[6:7], off offset:2176
	global_load_dwordx4 v[110:113], v[6:7], off offset:2192
	ds_read_b128 v[20:23], v10 offset:1536
	ds_read_b128 v[24:27], v10 offset:1552
	ds_read_b128 v[28:31], v10 offset:1664
	ds_read_b128 v[32:35], v10 offset:1680
	s_waitcnt vmcnt(18)
	s_waitcnt lgkmcnt(4)
; DI_ unsigned pk2(float lo, float hi) { typedef float f2 __attribute__((ext_vector_type(2))); typedef __bf16 b2 __attribute__((ext_vector_type(2))); f2 v = {lo, hi}; b2 b = __builtin_convertvector(v, b2); return __builtin_bit_cast(unsigned, b); }
; template <int NS, bool LN, bool WF32, bool WBF, int SKMODE>
; DI_ void row_pass(const float* Xin, float* Xout, bf16_t* XBo, const float* g, const float* b, const float* WsT, float* sk_out, const float* sk_bias, int row0, int nrows, int gw, int NGW, int lane) {
;     ...
;         if (WBF) {
;             u32x2* xo = (u32x2*)(XBo + (size_t)row * D) + lane;
; #pragma unroll
;             for (int j = 0; j < 4; ++j) { u32x2 w; w.x = pk2(v[j][0], v[j][1]); w.y = pk2(v[j][2], v[j][3]); xo[64 * j] = w; }
;         }
;         if (NS > 0) {
; #pragma unroll 1
;             for (int grp = 0; grp < NS / 8; ++grp) {
;                 float a[8];
; #pragma unroll
;                 for (int jc = 0; jc < 8; ++jc) {
;                     float s = 0.f;
; #pragma unroll
;                     for (int j = 0; j < 4; ++j) { const f32x4 w = *(const f32x4*)(WsT + (8 * grp + jc) * WST + 4 * (lane + 64 * j)); s += (v[j][0] * w[0] + v[j][1] * w[1]) + (v[j][2] * w[2] + v[j][3] * w[3]); }
	v_mfma_f32_16x16x4_f32 v[12:15], v114, v36, v[12:15]
	v_mfma_f32_16x16x4_f32 v[16:19], v115, v37, v[16:19]
	v_cvt_pk_bf16_f32 v60, v114, v115
	v_mfma_f32_16x16x4_f32 v[12:15], v116, v38, v[12:15]
	v_mfma_f32_16x16x4_f32 v[16:19], v117, v39, v[16:19]
	v_cvt_pk_bf16_f32 v61, v116, v117
	v_mfma_f32_16x16x4_f32 v[12:15], v118, v40, v[12:15]
	v_mfma_f32_16x16x4_f32 v[16:19], v119, v41, v[16:19]
	v_cvt_pk_bf16_f32 v62, v118, v119
	v_mfma_f32_16x16x4_f32 v[12:15], v120, v42, v[12:15]
	v_mfma_f32_16x16x4_f32 v[16:19], v121, v43, v[16:19]
	v_cvt_pk_bf16_f32 v63, v120, v121
	v_mfma_f32_16x16x4_f32 v[12:15], v122, v44, v[12:15]
	v_mfma_f32_16x16x4_f32 v[16:19], v123, v45, v[16:19]
	v_cvt_pk_bf16_f32 v64, v122, v123
	v_mfma_f32_16x16x4_f32 v[12:15], v124, v46, v[12:15]
	v_mfma_f32_16x16x4_f32 v[16:19], v125, v47, v[16:19]
	v_cvt_pk_bf16_f32 v65, v124, v125
	v_mfma_f32_16x16x4_f32 v[12:15], v126, v48, v[12:15]
	v_mfma_f32_16x16x4_f32 v[16:19], v127, v49, v[16:19]
	v_cvt_pk_bf16_f32 v66, v126, v127
	v_mfma_f32_16x16x4_f32 v[12:15], v128, v50, v[12:15]
	v_mfma_f32_16x16x4_f32 v[16:19], v129, v51, v[16:19]
	v_cvt_pk_bf16_f32 v67, v128, v129
	global_store_dwordx4 v[8:9], v[60:63], off offset:640
	global_store_dwordx4 v[8:9], v[64:67], off offset:704
	global_load_dwordx4 v[114:117], v[6:7], off offset:2304
	global_load_dwordx4 v[118:121], v[6:7], off offset:2320
	global_load_dwordx4 v[122:125], v[6:7], off offset:2432
	global_load_dwordx4 v[126:129], v[6:7], off offset:2448
	ds_read_b128 v[36:39], v10 offset:1792
	ds_read_b128 v[40:43], v10 offset:1808
	ds_read_b128 v[44:47], v10 offset:1920
	ds_read_b128 v[48:51], v10 offset:1936
	s_waitcnt vmcnt(18)
	s_waitcnt lgkmcnt(4)
	v_mfma_f32_16x16x4_f32 v[12:15], v130, v20, v[12:15]
	v_mfma_f32_16x16x4_f32 v[16:19], v131, v21, v[16:19]
	v_cvt_pk_bf16_f32 v52, v130, v131
	v_mfma_f32_16x16x4_f32 v[12:15], v132, v22, v[12:15]
	v_mfma_f32_16x16x4_f32 v[16:19], v133, v23, v[16:19]
	v_cvt_pk_bf16_f32 v53, v132, v133
	v_mfma_f32_16x16x4_f32 v[12:15], v134, v24, v[12:15]
	v_mfma_f32_16x16x4_f32 v[16:19], v135, v25, v[16:19]
	v_cvt_pk_bf16_f32 v54, v134, v135
	v_mfma_f32_16x16x4_f32 v[12:15], v136, v26, v[12:15]
	v_mfma_f32_16x16x4_f32 v[16:19], v137, v27, v[16:19]
	v_cvt_pk_bf16_f32 v55, v136, v137
	v_mfma_f32_16x16x4_f32 v[12:15], v138, v28, v[12:15]
	v_mfma_f32_16x16x4_f32 v[16:19], v139, v29, v[16:19]
	v_cvt_pk_bf16_f32 v56, v138, v139
	v_mfma_f32_16x16x4_f32 v[12:15], v140, v30, v[12:15]
	v_mfma_f32_16x16x4_f32 v[16:19], v141, v31, v[16:19]
	v_cvt_pk_bf16_f32 v57, v140, v141
	v_mfma_f32_16x16x4_f32 v[12:15], v142, v32, v[12:15]
	v_mfma_f32_16x16x4_f32 v[16:19], v143, v33, v[16:19]
	v_cvt_pk_bf16_f32 v58, v142, v143
	v_mfma_f32_16x16x4_f32 v[12:15], v144, v34, v[12:15]
	v_mfma_f32_16x16x4_f32 v[16:19], v145, v35, v[16:19]
	v_cvt_pk_bf16_f32 v59, v144, v145
	global_store_dwordx4 v[8:9], v[52:55], off offset:768
	global_store_dwordx4 v[8:9], v[56:59], off offset:832
	global_load_dwordx4 v[130:133], v[6:7], off offset:2560
	global_load_dwordx4 v[134:137], v[6:7], off offset:2576
	global_load_dwordx4 v[138:141], v[6:7], off offset:2688
	global_load_dwordx4 v[142:145], v[6:7], off offset:2704
	ds_read_b128 v[20:23], v10 offset:2048
	ds_read_b128 v[24:27], v10 offset:2064
	ds_read_b128 v[28:31], v10 offset:2176
	ds_read_b128 v[32:35], v10 offset:2192
	s_waitcnt vmcnt(18)
	s_waitcnt lgkmcnt(4)
	v_mfma_f32_16x16x4_f32 v[12:15], v150, v36, v[12:15]
	v_mfma_f32_16x16x4_f32 v[16:19], v151, v37, v[16:19]
	v_cvt_pk_bf16_f32 v60, v150, v151
	v_mfma_f32_16x16x4_f32 v[12:15], v152, v38, v[12:15]
	v_mfma_f32_16x16x4_f32 v[16:19], v153, v39, v[16:19]
	v_cvt_pk_bf16_f32 v61, v152, v153
	v_mfma_f32_16x16x4_f32 v[12:15], v154, v40, v[12:15]
	v_mfma_f32_16x16x4_f32 v[16:19], v155, v41, v[16:19]
	v_cvt_pk_bf16_f32 v62, v154, v155
	v_mfma_f32_16x16x4_f32 v[12:15], v156, v42, v[12:15]
	v_mfma_f32_16x16x4_f32 v[16:19], v157, v43, v[16:19]
	v_cvt_pk_bf16_f32 v63, v156, v157
	v_mfma_f32_16x16x4_f32 v[12:15], v158, v44, v[12:15]
	v_mfma_f32_16x16x4_f32 v[16:19], v159, v45, v[16:19]
	v_cvt_pk_bf16_f32 v64, v158, v159
	v_mfma_f32_16x16x4_f32 v[12:15], v160, v46, v[12:15]
	v_mfma_f32_16x16x4_f32 v[16:19], v161, v47, v[16:19]
	v_cvt_pk_bf16_f32 v65, v160, v161
	v_mfma_f32_16x16x4_f32 v[12:15], v162, v48, v[12:15]
	v_mfma_f32_16x16x4_f32 v[16:19], v163, v49, v[16:19]
	v_cvt_pk_bf16_f32 v66, v162, v163
	v_mfma_f32_16x16x4_f32 v[12:15], v164, v50, v[12:15]
	v_mfma_f32_16x16x4_f32 v[16:19], v165, v51, v[16:19]
	v_cvt_pk_bf16_f32 v67, v164, v165
	global_store_dwordx4 v[8:9], v[60:63], off offset:896
	global_store_dwordx4 v[8:9], v[64:67], off offset:960
	global_load_dwordx4 v[150:153], v[6:7], off offset:2816
	global_load_dwordx4 v[154:157], v[6:7], off offset:2832
	global_load_dwordx4 v[158:161], v[6:7], off offset:2944
	global_load_dwordx4 v[162:165], v[6:7], off offset:2960
	ds_read_b128 v[36:39], v10 offset:2304
	ds_read_b128 v[40:43], v10 offset:2320
	ds_read_b128 v[44:47], v10 offset:2432
	ds_read_b128 v[48:51], v10 offset:2448
	s_waitcnt vmcnt(18)
	s_waitcnt lgkmcnt(4)
; DI_ unsigned pk2(float lo, float hi) { typedef float f2 __attribute__((ext_vector_type(2))); typedef __bf16 b2 __attribute__((ext_vector_type(2))); f2 v = {lo, hi}; b2 b = __builtin_convertvector(v, b2); return __builtin_bit_cast(unsigned, b); }
; template <int NS, bool LN, bool WF32, bool WBF, int SKMODE>
; DI_ void row_pass(const float* Xin, float* Xout, bf16_t* XBo, const float* g, const float* b, const float* WsT, float* sk_out, const float* sk_bias, int row0, int nrows, int gw, int NGW, int lane) {
;     ...
;         if (WBF) {
;             u32x2* xo = (u32x2*)(XBo + (size_t)row * D) + lane;
; #pragma unroll
;             for (int j = 0; j < 4; ++j) { u32x2 w; w.x = pk2(v[j][0], v[j][1]); w.y = pk2(v[j][2], v[j][3]); xo[64 * j] = w; }
;         }
;         if (NS > 0) {
; #pragma unroll 1
;             for (int grp = 0; grp < NS / 8; ++grp) {
;                 float a[8];
; #pragma unroll
;                 for (int jc = 0; jc < 8; ++jc) {
;                     float s = 0.f;
; #pragma unroll
;                     for (int j = 0; j < 4; ++j) { const f32x4 w = *(const f32x4*)(WsT + (8 * grp + jc) * WST + 4 * (lane + 64 * j)); s += (v[j][0] * w[0] + v[j][1] * w[1]) + (v[j][2] * w[2] + v[j][3] * w[3]); }
	v_mfma_f32_16x16x4_f32 v[12:15], v98, v20, v[12:15]
	v_mfma_f32_16x16x4_f32 v[16:19], v99, v21, v[16:19]
	v_cvt_pk_bf16_f32 v52, v98, v99
	v_mfma_f32_16x16x4_f32 v[12:15], v100, v22, v[12:15]
	v_mfma_f32_16x16x4_f32 v[16:19], v101, v23, v[16:19]
	v_cvt_pk_bf16_f32 v53, v100, v101
	v_mfma_f32_16x16x4_f32 v[12:15], v102, v24, v[12:15]
	v_mfma_f32_16x16x4_f32 v[16:19], v103, v25, v[16:19]
	v_cvt_pk_bf16_f32 v54, v102, v103
	v_mfma_f32_16x16x4_f32 v[12:15], v104, v26, v[12:15]
	v_mfma_f32_16x16x4_f32 v[16:19], v105, v27, v[16:19]
	v_cvt_pk_bf16_f32 v55, v104, v105
	v_mfma_f32_16x16x4_f32 v[12:15], v106, v28, v[12:15]
	v_mfma_f32_16x16x4_f32 v[16:19], v107, v29, v[16:19]
	v_cvt_pk_bf16_f32 v56, v106, v107
	v_mfma_f32_16x16x4_f32 v[12:15], v108, v30, v[12:15]
	v_mfma_f32_16x16x4_f32 v[16:19], v109, v31, v[16:19]
	v_cvt_pk_bf16_f32 v57, v108, v109
	v_mfma_f32_16x16x4_f32 v[12:15], v110, v32, v[12:15]
	v_mfma_f32_16x16x4_f32 v[16:19], v111, v33, v[16:19]
	v_cvt_pk_bf16_f32 v58, v110, v111
	v_mfma_f32_16x16x4_f32 v[12:15], v112, v34, v[12:15]
	v_mfma_f32_16x16x4_f32 v[16:19], v113, v35, v[16:19]
	v_cvt_pk_bf16_f32 v59, v112, v113
	global_store_dwordx4 v[8:9], v[52:55], off offset:1024
	global_store_dwordx4 v[8:9], v[56:59], off offset:1088
	global_load_dwordx4 v[98:101], v[6:7], off offset:3072
	global_load_dwordx4 v[102:105], v[6:7], off offset:3088
	global_load_dwordx4 v[106:109], v[6:7], off offset:3200
	global_load_dwordx4 v[110:113], v[6:7], off offset:3216
	ds_read_b128 v[20:23], v10 offset:2560
	ds_read_b128 v[24:27], v10 offset:2576
	ds_read_b128 v[28:31], v10 offset:2688
	ds_read_b128 v[32:35], v10 offset:2704
	s_waitcnt vmcnt(18)
	s_waitcnt lgkmcnt(4)
	v_mfma_f32_16x16x4_f32 v[12:15], v114, v36, v[12:15]
	v_mfma_f32_16x16x4_f32 v[16:19], v115, v37, v[16:19]
	v_cvt_pk_bf16_f32 v60, v114, v115
	v_mfma_f32_16x16x4_f32 v[12:15], v116, v38, v[12:15]
	v_mfma_f32_16x16x4_f32 v[16:19], v117, v39, v[16:19]
	v_cvt_pk_bf16_f32 v61, v116, v117
	v_mfma_f32_16x16x4_f32 v[12:15], v118, v40, v[12:15]
	v_mfma_f32_16x16x4_f32 v[16:19], v119, v41, v[16:19]
	v_cvt_pk_bf16_f32 v62, v118, v119
	v_mfma_f32_16x16x4_f32 v[12:15], v120, v42, v[12:15]
	v_mfma_f32_16x16x4_f32 v[16:19], v121, v43, v[16:19]
	v_cvt_pk_bf16_f32 v63, v120, v121
	v_mfma_f32_16x16x4_f32 v[12:15], v122, v44, v[12:15]
	v_mfma_f32_16x16x4_f32 v[16:19], v123, v45, v[16:19]
	v_cvt_pk_bf16_f32 v64, v122, v123
	v_mfma_f32_16x16x4_f32 v[12:15], v124, v46, v[12:15]
	v_mfma_f32_16x16x4_f32 v[16:19], v125, v47, v[16:19]
	v_cvt_pk_bf16_f32 v65, v124, v125
	v_mfma_f32_16x16x4_f32 v[12:15], v126, v48, v[12:15]
	v_mfma_f32_16x16x4_f32 v[16:19], v127, v49, v[16:19]
	v_cvt_pk_bf16_f32 v66, v126, v127
	v_mfma_f32_16x16x4_f32 v[12:15], v128, v50, v[12:15]
	v_mfma_f32_16x16x4_f32 v[16:19], v129, v51, v[16:19]
	v_cvt_pk_bf16_f32 v67, v128, v129
	global_store_dwordx4 v[8:9], v[60:63], off offset:1152
	global_store_dwordx4 v[8:9], v[64:67], off offset:1216
	global_load_dwordx4 v[114:117], v[6:7], off offset:3328
	global_load_dwordx4 v[118:121], v[6:7], off offset:3344
	global_load_dwordx4 v[122:125], v[6:7], off offset:3456
	global_load_dwordx4 v[126:129], v[6:7], off offset:3472
	ds_read_b128 v[36:39], v10 offset:2816
	ds_read_b128 v[40:43], v10 offset:2832
	ds_read_b128 v[44:47], v10 offset:2944
	ds_read_b128 v[48:51], v10 offset:2960
	s_waitcnt vmcnt(18)
	s_waitcnt lgkmcnt(4)
	v_mfma_f32_16x16x4_f32 v[12:15], v130, v20, v[12:15]
	v_mfma_f32_16x16x4_f32 v[16:19], v131, v21, v[16:19]
	v_cvt_pk_bf16_f32 v52, v130, v131
	v_mfma_f32_16x16x4_f32 v[12:15], v132, v22, v[12:15]
	v_mfma_f32_16x16x4_f32 v[16:19], v133, v23, v[16:19]
	v_cvt_pk_bf16_f32 v53, v132, v133
	v_mfma_f32_16x16x4_f32 v[12:15], v134, v24, v[12:15]
	v_mfma_f32_16x16x4_f32 v[16:19], v135, v25, v[16:19]
	v_cvt_pk_bf16_f32 v54, v134, v135
	v_mfma_f32_16x16x4_f32 v[12:15], v136, v26, v[12:15]
	v_mfma_f32_16x16x4_f32 v[16:19], v137, v27, v[16:19]
	v_cvt_pk_bf16_f32 v55, v136, v137
	v_mfma_f32_16x16x4_f32 v[12:15], v138, v28, v[12:15]
	v_mfma_f32_16x16x4_f32 v[16:19], v139, v29, v[16:19]
	v_cvt_pk_bf16_f32 v56, v138, v139
	v_mfma_f32_16x16x4_f32 v[12:15], v140, v30, v[12:15]
	v_mfma_f32_16x16x4_f32 v[16:19], v141, v31, v[16:19]
	v_cvt_pk_bf16_f32 v57, v140, v141
	v_mfma_f32_16x16x4_f32 v[12:15], v142, v32, v[12:15]
	v_mfma_f32_16x16x4_f32 v[16:19], v143, v33, v[16:19]
	v_cvt_pk_bf16_f32 v58, v142, v143
	v_mfma_f32_16x16x4_f32 v[12:15], v144, v34, v[12:15]
	v_mfma_f32_16x16x4_f32 v[16:19], v145, v35, v[16:19]
	v_cvt_pk_bf16_f32 v59, v144, v145
	global_store_dwordx4 v[8:9], v[52:55], off offset:1280
	global_store_dwordx4 v[8:9], v[56:59], off offset:1344
	global_load_dwordx4 v[130:133], v[6:7], off offset:3584
	global_load_dwordx4 v[134:137], v[6:7], off offset:3600
	global_load_dwordx4 v[138:141], v[6:7], off offset:3712
	global_load_dwordx4 v[142:145], v[6:7], off offset:3728
	ds_read_b128 v[20:23], v10 offset:3072
	ds_read_b128 v[24:27], v10 offset:3088
	ds_read_b128 v[28:31], v10 offset:3200
	ds_read_b128 v[32:35], v10 offset:3216
	s_waitcnt vmcnt(18)
	s_waitcnt lgkmcnt(4)
; DI_ unsigned pk2(float lo, float hi) { typedef float f2 __attribute__((ext_vector_type(2))); typedef __bf16 b2 __attribute__((ext_vector_type(2))); f2 v = {lo, hi}; b2 b = __builtin_convertvector(v, b2); return __builtin_bit_cast(unsigned, b); }
; template <int NS, bool LN, bool WF32, bool WBF, int SKMODE>
; DI_ void row_pass(const float* Xin, float* Xout, bf16_t* XBo, const float* g, const float* b, const float* WsT, float* sk_out, const float* sk_bias, int row0, int nrows, int gw, int NGW, int lane) {
;     ...
;         if (WBF) {
;             u32x2* xo = (u32x2*)(XBo + (size_t)row * D) + lane;
; #pragma unroll
;             for (int j = 0; j < 4; ++j) { u32x2 w; w.x = pk2(v[j][0], v[j][1]); w.y = pk2(v[j][2], v[j][3]); xo[64 * j] = w; }
;         }
;         if (NS > 0) {
; #pragma unroll 1
;             for (int grp = 0; grp < NS / 8; ++grp) {
;                 float a[8];
; #pragma unroll
;                 for (int jc = 0; jc < 8; ++jc) {
;                     float s = 0.f;
; #pragma unroll
;                     for (int j = 0; j < 4; ++j) { const f32x4 w = *(const f32x4*)(WsT + (8 * grp + jc) * WST + 4 * (lane + 64 * j)); s += (v[j][0] * w[0] + v[j][1] * w[1]) + (v[j][2] * w[2] + v[j][3] * w[3]); }
	v_mfma_f32_16x16x4_f32 v[12:15], v150, v36, v[12:15]
	v_mfma_f32_16x16x4_f32 v[16:19], v151, v37, v[16:19]
	v_cvt_pk_bf16_f32 v60, v150, v151
	v_mfma_f32_16x16x4_f32 v[12:15], v152, v38, v[12:15]
	v_mfma_f32_16x16x4_f32 v[16:19], v153, v39, v[16:19]
	v_cvt_pk_bf16_f32 v61, v152, v153
	v_mfma_f32_16x16x4_f32 v[12:15], v154, v40, v[12:15]
	v_mfma_f32_16x16x4_f32 v[16:19], v155, v41, v[16:19]
	v_cvt_pk_bf16_f32 v62, v154, v155
	v_mfma_f32_16x16x4_f32 v[12:15], v156, v42, v[12:15]
	v_mfma_f32_16x16x4_f32 v[16:19], v157, v43, v[16:19]
	v_cvt_pk_bf16_f32 v63, v156, v157
	v_mfma_f32_16x16x4_f32 v[12:15], v158, v44, v[12:15]
	v_mfma_f32_16x16x4_f32 v[16:19], v159, v45, v[16:19]
	v_cvt_pk_bf16_f32 v64, v158, v159
	v_mfma_f32_16x16x4_f32 v[12:15], v160, v46, v[12:15]
	v_mfma_f32_16x16x4_f32 v[16:19], v161, v47, v[16:19]
	v_cvt_pk_bf16_f32 v65, v160, v161
	v_mfma_f32_16x16x4_f32 v[12:15], v162, v48, v[12:15]
	v_mfma_f32_16x16x4_f32 v[16:19], v163, v49, v[16:19]
	v_cvt_pk_bf16_f32 v66, v162, v163
	v_mfma_f32_16x16x4_f32 v[12:15], v164, v50, v[12:15]
	v_mfma_f32_16x16x4_f32 v[16:19], v165, v51, v[16:19]
	v_cvt_pk_bf16_f32 v67, v164, v165
	global_store_dwordx4 v[8:9], v[60:63], off offset:1408
	global_store_dwordx4 v[8:9], v[64:67], off offset:1472
	global_load_dwordx4 v[150:153], v[6:7], off offset:3840
	global_load_dwordx4 v[154:157], v[6:7], off offset:3856
	global_load_dwordx4 v[158:161], v[6:7], off offset:3968
	global_load_dwordx4 v[162:165], v[6:7], off offset:3984
	ds_read_b128 v[36:39], v10 offset:3328
	ds_read_b128 v[40:43], v10 offset:3344
	ds_read_b128 v[44:47], v10 offset:3456
	ds_read_b128 v[48:51], v10 offset:3472
	s_waitcnt vmcnt(18)
	s_waitcnt lgkmcnt(4)
	v_mfma_f32_16x16x4_f32 v[12:15], v98, v20, v[12:15]
	v_mfma_f32_16x16x4_f32 v[16:19], v99, v21, v[16:19]
	v_cvt_pk_bf16_f32 v52, v98, v99
	v_mfma_f32_16x16x4_f32 v[12:15], v100, v22, v[12:15]
	v_mfma_f32_16x16x4_f32 v[16:19], v101, v23, v[16:19]
	v_cvt_pk_bf16_f32 v53, v100, v101
	v_mfma_f32_16x16x4_f32 v[12:15], v102, v24, v[12:15]
	v_mfma_f32_16x16x4_f32 v[16:19], v103, v25, v[16:19]
	v_cvt_pk_bf16_f32 v54, v102, v103
	v_mfma_f32_16x16x4_f32 v[12:15], v104, v26, v[12:15]
	v_mfma_f32_16x16x4_f32 v[16:19], v105, v27, v[16:19]
	v_cvt_pk_bf16_f32 v55, v104, v105
	v_mfma_f32_16x16x4_f32 v[12:15], v106, v28, v[12:15]
	v_mfma_f32_16x16x4_f32 v[16:19], v107, v29, v[16:19]
	v_cvt_pk_bf16_f32 v56, v106, v107
	v_mfma_f32_16x16x4_f32 v[12:15], v108, v30, v[12:15]
	v_mfma_f32_16x16x4_f32 v[16:19], v109, v31, v[16:19]
	v_cvt_pk_bf16_f32 v57, v108, v109
	v_mfma_f32_16x16x4_f32 v[12:15], v110, v32, v[12:15]
	v_mfma_f32_16x16x4_f32 v[16:19], v111, v33, v[16:19]
	v_cvt_pk_bf16_f32 v58, v110, v111
	v_mfma_f32_16x16x4_f32 v[12:15], v112, v34, v[12:15]
	v_mfma_f32_16x16x4_f32 v[16:19], v113, v35, v[16:19]
	v_cvt_pk_bf16_f32 v59, v112, v113
	global_store_dwordx4 v[8:9], v[52:55], off offset:1536
	global_store_dwordx4 v[8:9], v[56:59], off offset:1600
	ds_read_b128 v[20:23], v10 offset:3584
	ds_read_b128 v[24:27], v10 offset:3600
	ds_read_b128 v[28:31], v10 offset:3712
	ds_read_b128 v[32:35], v10 offset:3728
	s_waitcnt vmcnt(14)
	s_waitcnt lgkmcnt(4)
	v_mfma_f32_16x16x4_f32 v[12:15], v114, v36, v[12:15]
	v_mfma_f32_16x16x4_f32 v[16:19], v115, v37, v[16:19]
	v_cvt_pk_bf16_f32 v60, v114, v115
	v_mfma_f32_16x16x4_f32 v[12:15], v116, v38, v[12:15]
	v_mfma_f32_16x16x4_f32 v[16:19], v117, v39, v[16:19]
	v_cvt_pk_bf16_f32 v61, v116, v117
	v_mfma_f32_16x16x4_f32 v[12:15], v118, v40, v[12:15]
	v_mfma_f32_16x16x4_f32 v[16:19], v119, v41, v[16:19]
	v_cvt_pk_bf16_f32 v62, v118, v119
	v_mfma_f32_16x16x4_f32 v[12:15], v120, v42, v[12:15]
	v_mfma_f32_16x16x4_f32 v[16:19], v121, v43, v[16:19]
	v_cvt_pk_bf16_f32 v63, v120, v121
	v_mfma_f32_16x16x4_f32 v[12:15], v122, v44, v[12:15]
	v_mfma_f32_16x16x4_f32 v[16:19], v123, v45, v[16:19]
	v_cvt_pk_bf16_f32 v64, v122, v123
	v_mfma_f32_16x16x4_f32 v[12:15], v124, v46, v[12:15]
	v_mfma_f32_16x16x4_f32 v[16:19], v125, v47, v[16:19]
	v_cvt_pk_bf16_f32 v65, v124, v125
	v_mfma_f32_16x16x4_f32 v[12:15], v126, v48, v[12:15]
	v_mfma_f32_16x16x4_f32 v[16:19], v127, v49, v[16:19]
	v_cvt_pk_bf16_f32 v66, v126, v127
	v_mfma_f32_16x16x4_f32 v[12:15], v128, v50, v[12:15]
	v_mfma_f32_16x16x4_f32 v[16:19], v129, v51, v[16:19]
	v_cvt_pk_bf16_f32 v67, v128, v129
	global_store_dwordx4 v[8:9], v[60:63], off offset:1664
	global_store_dwordx4 v[8:9], v[64:67], off offset:1728
	ds_read_b128 v[36:39], v10 offset:3840
	ds_read_b128 v[40:43], v10 offset:3856
	ds_read_b128 v[44:47], v10 offset:3968
	ds_read_b128 v[48:51], v10 offset:3984
	s_waitcnt vmcnt(10)
	s_waitcnt lgkmcnt(4)
	v_mfma_f32_16x16x4_f32 v[12:15], v130, v20, v[12:15]
	v_mfma_f32_16x16x4_f32 v[16:19], v131, v21, v[16:19]
	v_cvt_pk_bf16_f32 v52, v130, v131
	v_mfma_f32_16x16x4_f32 v[12:15], v132, v22, v[12:15]
	v_mfma_f32_16x16x4_f32 v[16:19], v133, v23, v[16:19]
	v_cvt_pk_bf16_f32 v53, v132, v133
	v_mfma_f32_16x16x4_f32 v[12:15], v134, v24, v[12:15]
	v_mfma_f32_16x16x4_f32 v[16:19], v135, v25, v[16:19]
	v_cvt_pk_bf16_f32 v54, v134, v135
	v_mfma_f32_16x16x4_f32 v[12:15], v136, v26, v[12:15]
	v_mfma_f32_16x16x4_f32 v[16:19], v137, v27, v[16:19]
	v_cvt_pk_bf16_f32 v55, v136, v137
	v_mfma_f32_16x16x4_f32 v[12:15], v138, v28, v[12:15]
	v_mfma_f32_16x16x4_f32 v[16:19], v139, v29, v[16:19]
	v_cvt_pk_bf16_f32 v56, v138, v139
	v_mfma_f32_16x16x4_f32 v[12:15], v140, v30, v[12:15]
	v_mfma_f32_16x16x4_f32 v[16:19], v141, v31, v[16:19]
	v_cvt_pk_bf16_f32 v57, v140, v141
	v_mfma_f32_16x16x4_f32 v[12:15], v142, v32, v[12:15]
	v_mfma_f32_16x16x4_f32 v[16:19], v143, v33, v[16:19]
	v_cvt_pk_bf16_f32 v58, v142, v143
	v_mfma_f32_16x16x4_f32 v[12:15], v144, v34, v[12:15]
	v_mfma_f32_16x16x4_f32 v[16:19], v145, v35, v[16:19]
	v_cvt_pk_bf16_f32 v59, v144, v145
	global_store_dwordx4 v[8:9], v[52:55], off offset:1792
	global_store_dwordx4 v[8:9], v[56:59], off offset:1856
	s_waitcnt vmcnt(6)
; DI_ float log_sigmoid(float v) { return fminf(v, 0.f) - log1pf(expf(-fabsf(v))); }
; template <int NS, bool LN, bool WF32, bool WBF, int SKMODE>
; DI_ void row_pass(const float* Xin, float* Xout, bf16_t* XBo, const float* g, const float* b, const float* WsT, float* sk_out, const float* sk_bias, int row0, int nrows, int gw, int NGW, int lane) {
;     ...
;                     for (int j = 0; j < 4; ++j) { const f32x4 w = *(const f32x4*)(WsT + (8 * grp + jc) * WST + 4 * (lane + 64 * j)); s += (v[j][0] * w[0] + v[j][1] * w[1]) + (v[j][2] * w[2] + v[j][3] * w[3]); }
;                     a[jc] = s;
;                 }
;                 { const bool up = (lane & 32) != 0;
; #pragma unroll
;                   for (int i = 0; i < 4; ++i) { const float send = up ? a[i] : a[4 + i], keep = up ? a[4 + i] : a[i]; a[i] = keep + __shfl_xor(send, 32); } }
;                 { const bool up = (lane & 16) != 0;
; #pragma unroll
;                   for (int i = 0; i < 2; ++i) { const float send = up ? a[i] : a[2 + i], keep = up ? a[2 + i] : a[i]; a[i] = keep + __shfl_xor(send, 16); } }
;                 { const bool up = (lane & 8) != 0; const float send = up ? a[0] : a[1], keep = up ? a[1] : a[0]; a[0] = keep + __shfl_xor(send, 8); }
;                 a[0] += __shfl_xor(a[0], 4); a[0] += __shfl_xor(a[0], 2); a[0] += __shfl_xor(a[0], 1);
;                 const int jo = 8 * grp + (lane >> 3);
;                 if ((lane & 7) == 0) sk_out[(size_t)row * NS + jo] = (SKMODE == 1) ? log_sigmoid(a[0] + sk_bias[jo]) : a[0];
	s_waitcnt lgkmcnt(0)
	v_mfma_f32_16x16x4_f32 v[12:15], v150, v36, v[12:15]
	v_mfma_f32_16x16x4_f32 v[16:19], v151, v37, v[16:19]
	v_cvt_pk_bf16_f32 v60, v150, v151
	v_mfma_f32_16x16x4_f32 v[12:15], v152, v38, v[12:15]
	v_mfma_f32_16x16x4_f32 v[16:19], v153, v39, v[16:19]
	v_cvt_pk_bf16_f32 v61, v152, v153
	v_mfma_f32_16x16x4_f32 v[12:15], v154, v40, v[12:15]
	v_mfma_f32_16x16x4_f32 v[16:19], v155, v41, v[16:19]
	v_cvt_pk_bf16_f32 v62, v154, v155
	v_mfma_f32_16x16x4_f32 v[12:15], v156, v42, v[12:15]
	v_mfma_f32_16x16x4_f32 v[16:19], v157, v43, v[16:19]
	v_cvt_pk_bf16_f32 v63, v156, v157
	v_mfma_f32_16x16x4_f32 v[12:15], v158, v44, v[12:15]
	v_mfma_f32_16x16x4_f32 v[16:19], v159, v45, v[16:19]
	v_cvt_pk_bf16_f32 v64, v158, v159
	v_mfma_f32_16x16x4_f32 v[12:15], v160, v46, v[12:15]
	v_mfma_f32_16x16x4_f32 v[16:19], v161, v47, v[16:19]
	v_cvt_pk_bf16_f32 v65, v160, v161
	v_mfma_f32_16x16x4_f32 v[12:15], v162, v48, v[12:15]
	v_mfma_f32_16x16x4_f32 v[16:19], v163, v49, v[16:19]
	v_cvt_pk_bf16_f32 v66, v162, v163
	v_mfma_f32_16x16x4_f32 v[12:15], v164, v50, v[12:15]
	v_mfma_f32_16x16x4_f32 v[16:19], v165, v51, v[16:19]
	v_cvt_pk_bf16_f32 v67, v164, v165
	global_store_dwordx4 v[8:9], v[60:63], off offset:1920
	global_store_dwordx4 v[8:9], v[64:67], off offset:1984
	s_nop 15
	v_add_f32_e32 v12, v12, v16
	v_add_f32_e32 v13, v13, v17
	v_add_f32_e32 v14, v14, v18
	v_add_f32_e32 v15, v15, v19
	v_lshl_add_u32 v22, v3, 2, s0
	v_lshlrev_b32_e32 v22, 6, v22
	v_lshl_add_u32 v22, v2, 2, v22
	v_mov_b32_e32 v23, 0
	v_mov_b32_e32 v4, s3
	v_mov_b32_e32 v5, s33
	v_lshl_add_u64 v[22:23], v[4:5], 0, v[22:23]
	global_load_dword v24, v11, s[62:63]
	s_mov_b32 s28, 0xbfb8aa3b
	s_mov_b32 s29, 0xb2a5705f
	s_mov_b32 s30, 0x42ce8ed0
	s_mov_b32 s31, 0xc2b17218
	s_mov_b32 s34, 0x7f800000
	s_mov_b32 s35, 0x3f2aaaab
	s_mov_b32 s36, 0x3f317218
	s_mov_b32 s37, 0x33800000
	v_mov_b32_e32 v49, 0x3ecc95a3
	v_mov_b32_e32 v50, 0x7f800000
	v_mov_b32_e32 v40, 0x3f317218
	s_waitcnt vmcnt(0)
	v_add_f32_e32 v34, v12, v24
	v_mul_f32_e64 v41, |v34|, s28
	v_fma_f32 v51, |v34|, s28, -v41
	v_rndne_f32_e32 v54, v41
	v_fma_f32 v51, |v34|, s29, v51
	v_sub_f32_e32 v41, v41, v54
	v_add_f32_e32 v41, v41, v51
	v_cvt_i32_f32_e32 v54, v54
	v_exp_f32_e32 v41, v41
	v_cmp_ngt_f32_e64 vcc, |v34|, s30
	v_min_f32_e32 v51, 0, v34
	v_ldexp_f32 v41, v41, v54
	v_cndmask_b32_e32 v41, 0, v41, vcc
	v_cmp_nlt_f32_e64 vcc, |v34|, s31
	s_nop 1
	v_cndmask_b32_e32 v34, v50, v41, vcc
	v_add_f32_e32 v41, 1.0, v34
	v_add_f32_e32 v56, -1.0, v41
	v_frexp_mant_f32_e32 v57, v41
	v_cvt_f64_f32_e32 v[54:55], v41
	v_sub_f32_e32 v58, v56, v41
	v_frexp_exp_i32_f64_e32 v54, v[54:55]
	v_cmp_gt_f32_e32 vcc, s35, v57
	v_sub_f32_e32 v56, v34, v56
	v_add_f32_e32 v55, 1.0, v58
	v_subbrev_co_u32_e32 v54, vcc, 0, v54, vcc
	v_add_f32_e32 v55, v56, v55
	v_sub_u32_e32 v56, 0, v54
	v_ldexp_f32 v41, v41, v56
	v_ldexp_f32 v55, v55, v56
	v_add_f32_e32 v56, -1.0, v41
	v_add_f32_e32 v58, 1.0, v41
	v_add_f32_e32 v57, 1.0, v56
	v_add_f32_e32 v59, -1.0, v58
	v_sub_f32_e32 v57, v41, v57
	v_sub_f32_e32 v41, v41, v59
	v_add_f32_e32 v41, v55, v41
	v_add_f32_e32 v59, v55, v57
	v_add_f32_e32 v55, v58, v41
	v_rcp_f32_e32 v62, v55
	v_add_f32_e32 v57, v56, v59
	v_sub_f32_e32 v58, v58, v55
	v_add_f32_e32 v41, v41, v58
	v_mul_f32_e32 v64, v57, v62
	v_mul_f32_e32 v58, v55, v64
	v_fma_f32 v60, v64, v55, -v58
	v_sub_f32_e32 v56, v56, v57
	v_fmac_f32_e32 v60, v64, v41
	v_add_f32_e32 v63, v59, v56
	v_add_f32_e32 v56, v58, v60
	v_sub_f32_e32 v59, v57, v56
	v_mov_b32_e32 v61, v56
	v_pk_add_f32 v[56:57], v[56:57], v[58:59] neg_lo:[0,1] neg_hi:[0,1]
	v_cvt_f32_i32_e32 v54, v54
	v_pk_add_f32 v[56:57], v[56:57], v[60:61] neg_lo:[0,1] neg_hi:[0,1]
	v_cmp_neq_f32_e32 vcc, s34, v34
	v_add_f32_e32 v57, v63, v57
	v_add_f32_e32 v56, v56, v57
	v_add_f32_e32 v57, v59, v56
	v_mul_f32_e32 v61, v62, v57
	v_mul_f32_e32 v58, v55, v61
	v_fma_f32 v60, v61, v55, -v58
	v_sub_f32_e32 v59, v59, v57
	v_fmac_f32_e32 v60, v61, v41
	v_add_f32_e32 v63, v56, v59
	v_add_f32_e32 v65, v64, v61
	v_add_f32_e32 v56, v58, v60
	v_sub_f32_e32 v55, v65, v64
	v_sub_f32_e32 v59, v57, v56
	v_sub_f32_e32 v41, v61, v55
	v_mov_b32_e32 v61, v56
	v_pk_add_f32 v[56:57], v[56:57], v[58:59] neg_lo:[0,1] neg_hi:[0,1]
	s_nop 0
	v_pk_add_f32 v[56:57], v[56:57], v[60:61] neg_lo:[0,1] neg_hi:[0,1]
	s_nop 0
	v_add_f32_e32 v55, v63, v57
	v_add_f32_e32 v55, v56, v55
	v_add_f32_e32 v55, v59, v55
	v_mul_f32_e32 v55, v62, v55
	v_add_f32_e32 v41, v41, v55
	v_add_f32_e32 v55, v65, v41
	v_mul_f32_e32 v56, v55, v55
	v_sub_f32_e32 v58, v55, v65
	v_fmamk_f32 v59, v56, 0x3e9b6dac, v49
	v_ldexp_f32 v57, v55, 1
	v_sub_f32_e32 v58, v41, v58
	v_mul_f32_e32 v55, v55, v56
	v_fmaak_f32 v41, v56, v59, 0x3f2aaada
	v_ldexp_f32 v61, v58, 1
	v_pk_mul_f32 v[58:59], v[54:55], v[40:41]
	s_nop 0
	v_fma_f32 v56, v54, s36, -v58
	v_fmac_f32_e32 v56, 0xb102e308, v54
	v_pk_add_f32 v[54:55], v[58:59], v[56:57]
	v_mov_b32_e32 v60, v58
	v_sub_f32_e32 v41, v55, v57
	v_sub_f32_e32 v41, v59, v41
	v_add_f32_e32 v61, v61, v41
	v_pk_add_f32 v[62:63], v[54:55], v[58:59] neg_lo:[0,1] neg_hi:[0,1]
	v_pk_add_f32 v[58:59], v[54:55], v[60:61]
	v_mov_b32_e32 v57, v54
	v_mov_b32_e32 v63, v59
	v_pk_add_f32 v[66:67], v[56:57], v[62:63] neg_lo:[0,1] neg_hi:[0,1]
	v_pk_add_f32 v[56:57], v[56:57], v[62:63]
	v_mov_b32_e32 v65, v54
	v_pk_add_f32 v[62:63], v[56:57], v[54:55] op_sel:[1,0] op_sel_hi:[0,1] neg_lo:[0,1] neg_hi:[0,1]
	v_mov_b32_e32 v64, v61
	v_mov_b32_e32 v60, v59
	v_mov_b32_e32 v61, v57
	v_pk_mov_b32 v[54:55], v[54:55], v[62:63] op_sel:[1,0]
	v_pk_add_f32 v[58:59], v[58:59], v[62:63] op_sel_hi:[1,0] neg_lo:[0,1] neg_hi:[0,1]
	v_pk_add_f32 v[54:55], v[60:61], v[54:55] neg_lo:[0,1] neg_hi:[0,1]
; DI_ float log_sigmoid(float v) { return fminf(v, 0.f) - log1pf(expf(-fabsf(v))); }
; template <int NS, bool LN, bool WF32, bool WBF, int SKMODE>
; DI_ void row_pass(const float* Xin, float* Xout, bf16_t* XBo, const float* g, const float* b, const float* WsT, float* sk_out, const float* sk_bias, int row0, int nrows, int gw, int NGW, int lane) {
;     ...
;                 if ((lane & 7) == 0) sk_out[(size_t)row * NS + jo] = (SKMODE == 1) ? log_sigmoid(a[0] + sk_bias[jo]) : a[0];
	v_mov_b32_e32 v58, v66
	v_pk_add_f32 v[54:55], v[64:65], v[54:55] neg_lo:[0,1] neg_hi:[0,1]
	v_mov_b32_e32 v67, v57
	v_pk_add_f32 v[58:59], v[58:59], v[54:55]
	s_nop 0
	v_pk_add_f32 v[60:61], v[58:59], v[58:59] op_sel:[0,1] op_sel_hi:[1,0]
	s_nop 0
	v_pk_add_f32 v[56:57], v[56:57], v[60:61] op_sel:[1,0] op_sel_hi:[0,1]
	v_mov_b32_e32 v59, v56
	v_mov_b32_e32 v55, v60
	v_pk_add_f32 v[60:61], v[58:59], v[66:67] neg_lo:[0,1] neg_hi:[0,1]
	s_nop 0
	v_sub_f32_e32 v41, v58, v60
	v_pk_add_f32 v[54:55], v[54:55], v[60:61] neg_lo:[0,1] neg_hi:[0,1]
	v_sub_f32_e32 v41, v66, v41
	v_add_f32_e32 v41, v54, v41
	v_add_f32_e32 v41, v41, v55
	v_add_f32_e32 v41, v56, v41
	v_cndmask_b32_e32 v41, v50, v41, vcc
	v_cmp_lt_f32_e64 vcc, |v34|, s37
	s_nop 1
	v_cndmask_b32_e32 v34, v41, v34, vcc
	v_sub_f32_e32 v34, v51, v34
	global_store_dword v[22:23], v34, off
	v_add_f32_e32 v34, v13, v24
	v_mul_f32_e64 v41, |v34|, s28
	v_fma_f32 v51, |v34|, s28, -v41
	v_rndne_f32_e32 v54, v41
	v_fma_f32 v51, |v34|, s29, v51
	v_sub_f32_e32 v41, v41, v54
	v_add_f32_e32 v41, v41, v51
	v_cvt_i32_f32_e32 v54, v54
	v_exp_f32_e32 v41, v41
	v_cmp_ngt_f32_e64 vcc, |v34|, s30
	v_min_f32_e32 v51, 0, v34
	v_ldexp_f32 v41, v41, v54
	v_cndmask_b32_e32 v41, 0, v41, vcc
	v_cmp_nlt_f32_e64 vcc, |v34|, s31
	s_nop 1
	v_cndmask_b32_e32 v34, v50, v41, vcc
	v_add_f32_e32 v41, 1.0, v34
	v_add_f32_e32 v56, -1.0, v41
	v_frexp_mant_f32_e32 v57, v41
	v_cvt_f64_f32_e32 v[54:55], v41
	v_sub_f32_e32 v58, v56, v41
	v_frexp_exp_i32_f64_e32 v54, v[54:55]
	v_cmp_gt_f32_e32 vcc, s35, v57
	v_sub_f32_e32 v56, v34, v56
	v_add_f32_e32 v55, 1.0, v58
	v_subbrev_co_u32_e32 v54, vcc, 0, v54, vcc
	v_add_f32_e32 v55, v56, v55
	v_sub_u32_e32 v56, 0, v54
	v_ldexp_f32 v41, v41, v56
	v_ldexp_f32 v55, v55, v56
	v_add_f32_e32 v56, -1.0, v41
	v_add_f32_e32 v58, 1.0, v41
	v_add_f32_e32 v57, 1.0, v56
	v_add_f32_e32 v59, -1.0, v58
	v_sub_f32_e32 v57, v41, v57
	v_sub_f32_e32 v41, v41, v59
	v_add_f32_e32 v41, v55, v41
	v_add_f32_e32 v59, v55, v57
	v_add_f32_e32 v55, v58, v41
	v_rcp_f32_e32 v62, v55
	v_add_f32_e32 v57, v56, v59
	v_sub_f32_e32 v58, v58, v55
	v_add_f32_e32 v41, v41, v58
	v_mul_f32_e32 v64, v57, v62
	v_mul_f32_e32 v58, v55, v64
	v_fma_f32 v60, v64, v55, -v58
	v_sub_f32_e32 v56, v56, v57
	v_fmac_f32_e32 v60, v64, v41
	v_add_f32_e32 v63, v59, v56
	v_add_f32_e32 v56, v58, v60
	v_sub_f32_e32 v59, v57, v56
	v_mov_b32_e32 v61, v56
	v_pk_add_f32 v[56:57], v[56:57], v[58:59] neg_lo:[0,1] neg_hi:[0,1]
	v_cvt_f32_i32_e32 v54, v54
	v_pk_add_f32 v[56:57], v[56:57], v[60:61] neg_lo:[0,1] neg_hi:[0,1]
	v_cmp_neq_f32_e32 vcc, s34, v34
	v_add_f32_e32 v57, v63, v57
	v_add_f32_e32 v56, v56, v57
	v_add_f32_e32 v57, v59, v56
	v_mul_f32_e32 v61, v62, v57
	v_mul_f32_e32 v58, v55, v61
	v_fma_f32 v60, v61, v55, -v58
	v_sub_f32_e32 v59, v59, v57
	v_fmac_f32_e32 v60, v61, v41
	v_add_f32_e32 v63, v56, v59
	v_add_f32_e32 v65, v64, v61
	v_add_f32_e32 v56, v58, v60
	v_sub_f32_e32 v55, v65, v64
	v_sub_f32_e32 v59, v57, v56
	v_sub_f32_e32 v41, v61, v55
	v_mov_b32_e32 v61, v56
	v_pk_add_f32 v[56:57], v[56:57], v[58:59] neg_lo:[0,1] neg_hi:[0,1]
	s_nop 0
	v_pk_add_f32 v[56:57], v[56:57], v[60:61] neg_lo:[0,1] neg_hi:[0,1]
	s_nop 0
	v_add_f32_e32 v55, v63, v57
	v_add_f32_e32 v55, v56, v55
	v_add_f32_e32 v55, v59, v55
	v_mul_f32_e32 v55, v62, v55
	v_add_f32_e32 v41, v41, v55
	v_add_f32_e32 v55, v65, v41
	v_mul_f32_e32 v56, v55, v55
	v_sub_f32_e32 v58, v55, v65
	v_fmamk_f32 v59, v56, 0x3e9b6dac, v49
	v_ldexp_f32 v57, v55, 1
	v_sub_f32_e32 v58, v41, v58
	v_mul_f32_e32 v55, v55, v56
	v_fmaak_f32 v41, v56, v59, 0x3f2aaada
	v_ldexp_f32 v61, v58, 1
	v_pk_mul_f32 v[58:59], v[54:55], v[40:41]
	s_nop 0
	v_fma_f32 v56, v54, s36, -v58
	v_fmac_f32_e32 v56, 0xb102e308, v54
	v_pk_add_f32 v[54:55], v[58:59], v[56:57]
	v_mov_b32_e32 v60, v58
	v_sub_f32_e32 v41, v55, v57
	v_sub_f32_e32 v41, v59, v41
	v_add_f32_e32 v61, v61, v41
	v_pk_add_f32 v[62:63], v[54:55], v[58:59] neg_lo:[0,1] neg_hi:[0,1]
	v_pk_add_f32 v[58:59], v[54:55], v[60:61]
	v_mov_b32_e32 v57, v54
	v_mov_b32_e32 v63, v59
	v_pk_add_f32 v[66:67], v[56:57], v[62:63] neg_lo:[0,1] neg_hi:[0,1]
	v_pk_add_f32 v[56:57], v[56:57], v[62:63]
	v_mov_b32_e32 v65, v54
	v_pk_add_f32 v[62:63], v[56:57], v[54:55] op_sel:[1,0] op_sel_hi:[0,1] neg_lo:[0,1] neg_hi:[0,1]
	v_mov_b32_e32 v64, v61
	v_mov_b32_e32 v60, v59
	v_mov_b32_e32 v61, v57
	v_pk_mov_b32 v[54:55], v[54:55], v[62:63] op_sel:[1,0]
	v_pk_add_f32 v[58:59], v[58:59], v[62:63] op_sel_hi:[1,0] neg_lo:[0,1] neg_hi:[0,1]
	v_pk_add_f32 v[54:55], v[60:61], v[54:55] neg_lo:[0,1] neg_hi:[0,1]
	v_mov_b32_e32 v58, v66
	v_pk_add_f32 v[54:55], v[64:65], v[54:55] neg_lo:[0,1] neg_hi:[0,1]
	v_mov_b32_e32 v67, v57
	v_pk_add_f32 v[58:59], v[58:59], v[54:55]
	s_nop 0
	v_pk_add_f32 v[60:61], v[58:59], v[58:59] op_sel:[0,1] op_sel_hi:[1,0]
	s_nop 0
	v_pk_add_f32 v[56:57], v[56:57], v[60:61] op_sel:[1,0] op_sel_hi:[0,1]
	v_mov_b32_e32 v59, v56
	v_mov_b32_e32 v55, v60
	v_pk_add_f32 v[60:61], v[58:59], v[66:67] neg_lo:[0,1] neg_hi:[0,1]
	s_nop 0
	v_sub_f32_e32 v41, v58, v60
	v_pk_add_f32 v[54:55], v[54:55], v[60:61] neg_lo:[0,1] neg_hi:[0,1]
	v_sub_f32_e32 v41, v66, v41
	v_add_f32_e32 v41, v54, v41
	v_add_f32_e32 v41, v41, v55
	v_add_f32_e32 v41, v56, v41
	v_cndmask_b32_e32 v41, v50, v41, vcc
	v_cmp_lt_f32_e64 vcc, |v34|, s37
	s_nop 1
	v_cndmask_b32_e32 v34, v41, v34, vcc
	v_sub_f32_e32 v34, v51, v34
	global_store_dword v[22:23], v34, off offset:64
	v_add_f32_e32 v34, v14, v24
	v_mul_f32_e64 v41, |v34|, s28
	v_fma_f32 v51, |v34|, s28, -v41
	v_rndne_f32_e32 v54, v41
	v_fma_f32 v51, |v34|, s29, v51
	v_sub_f32_e32 v41, v41, v54
	v_add_f32_e32 v41, v41, v51
	v_cvt_i32_f32_e32 v54, v54
; DI_ float log_sigmoid(float v) { return fminf(v, 0.f) - log1pf(expf(-fabsf(v))); }
; template <int NS, bool LN, bool WF32, bool WBF, int SKMODE>
; DI_ void row_pass(const float* Xin, float* Xout, bf16_t* XBo, const float* g, const float* b, const float* WsT, float* sk_out, const float* sk_bias, int row0, int nrows, int gw, int NGW, int lane) {
;     ...
;                 if ((lane & 7) == 0) sk_out[(size_t)row * NS + jo] = (SKMODE == 1) ? log_sigmoid(a[0] + sk_bias[jo]) : a[0];
	v_exp_f32_e32 v41, v41
	v_cmp_ngt_f32_e64 vcc, |v34|, s30
	v_min_f32_e32 v51, 0, v34
	v_ldexp_f32 v41, v41, v54
	v_cndmask_b32_e32 v41, 0, v41, vcc
	v_cmp_nlt_f32_e64 vcc, |v34|, s31
	s_nop 1
	v_cndmask_b32_e32 v34, v50, v41, vcc
	v_add_f32_e32 v41, 1.0, v34
	v_add_f32_e32 v56, -1.0, v41
	v_frexp_mant_f32_e32 v57, v41
	v_cvt_f64_f32_e32 v[54:55], v41
	v_sub_f32_e32 v58, v56, v41
	v_frexp_exp_i32_f64_e32 v54, v[54:55]
	v_cmp_gt_f32_e32 vcc, s35, v57
	v_sub_f32_e32 v56, v34, v56
	v_add_f32_e32 v55, 1.0, v58
	v_subbrev_co_u32_e32 v54, vcc, 0, v54, vcc
	v_add_f32_e32 v55, v56, v55
	v_sub_u32_e32 v56, 0, v54
	v_ldexp_f32 v41, v41, v56
	v_ldexp_f32 v55, v55, v56
	v_add_f32_e32 v56, -1.0, v41
	v_add_f32_e32 v58, 1.0, v41
	v_add_f32_e32 v57, 1.0, v56
	v_add_f32_e32 v59, -1.0, v58
	v_sub_f32_e32 v57, v41, v57
	v_sub_f32_e32 v41, v41, v59
	v_add_f32_e32 v41, v55, v41
	v_add_f32_e32 v59, v55, v57
	v_add_f32_e32 v55, v58, v41
	v_rcp_f32_e32 v62, v55
	v_add_f32_e32 v57, v56, v59
	v_sub_f32_e32 v58, v58, v55
	v_add_f32_e32 v41, v41, v58
	v_mul_f32_e32 v64, v57, v62
	v_mul_f32_e32 v58, v55, v64
	v_fma_f32 v60, v64, v55, -v58
	v_sub_f32_e32 v56, v56, v57
	v_fmac_f32_e32 v60, v64, v41
	v_add_f32_e32 v63, v59, v56
	v_add_f32_e32 v56, v58, v60
	v_sub_f32_e32 v59, v57, v56
	v_mov_b32_e32 v61, v56
	v_pk_add_f32 v[56:57], v[56:57], v[58:59] neg_lo:[0,1] neg_hi:[0,1]
	v_cvt_f32_i32_e32 v54, v54
	v_pk_add_f32 v[56:57], v[56:57], v[60:61] neg_lo:[0,1] neg_hi:[0,1]
	v_cmp_neq_f32_e32 vcc, s34, v34
	v_add_f32_e32 v57, v63, v57
	v_add_f32_e32 v56, v56, v57
	v_add_f32_e32 v57, v59, v56
	v_mul_f32_e32 v61, v62, v57
	v_mul_f32_e32 v58, v55, v61
	v_fma_f32 v60, v61, v55, -v58
	v_sub_f32_e32 v59, v59, v57
	v_fmac_f32_e32 v60, v61, v41
	v_add_f32_e32 v63, v56, v59
	v_add_f32_e32 v65, v64, v61
	v_add_f32_e32 v56, v58, v60
	v_sub_f32_e32 v55, v65, v64
	v_sub_f32_e32 v59, v57, v56
	v_sub_f32_e32 v41, v61, v55
	v_mov_b32_e32 v61, v56
	v_pk_add_f32 v[56:57], v[56:57], v[58:59] neg_lo:[0,1] neg_hi:[0,1]
	s_nop 0
	v_pk_add_f32 v[56:57], v[56:57], v[60:61] neg_lo:[0,1] neg_hi:[0,1]
	s_nop 0
	v_add_f32_e32 v55, v63, v57
	v_add_f32_e32 v55, v56, v55
	v_add_f32_e32 v55, v59, v55
	v_mul_f32_e32 v55, v62, v55
	v_add_f32_e32 v41, v41, v55
	v_add_f32_e32 v55, v65, v41
	v_mul_f32_e32 v56, v55, v55
	v_sub_f32_e32 v58, v55, v65
	v_fmamk_f32 v59, v56, 0x3e9b6dac, v49
	v_ldexp_f32 v57, v55, 1
	v_sub_f32_e32 v58, v41, v58
	v_mul_f32_e32 v55, v55, v56
	v_fmaak_f32 v41, v56, v59, 0x3f2aaada
	v_ldexp_f32 v61, v58, 1
	v_pk_mul_f32 v[58:59], v[54:55], v[40:41]
	s_nop 0
	v_fma_f32 v56, v54, s36, -v58
	v_fmac_f32_e32 v56, 0xb102e308, v54
	v_pk_add_f32 v[54:55], v[58:59], v[56:57]
	v_mov_b32_e32 v60, v58
	v_sub_f32_e32 v41, v55, v57
	v_sub_f32_e32 v41, v59, v41
	v_add_f32_e32 v61, v61, v41
	v_pk_add_f32 v[62:63], v[54:55], v[58:59] neg_lo:[0,1] neg_hi:[0,1]
	v_pk_add_f32 v[58:59], v[54:55], v[60:61]
	v_mov_b32_e32 v57, v54
	v_mov_b32_e32 v63, v59
	v_pk_add_f32 v[66:67], v[56:57], v[62:63] neg_lo:[0,1] neg_hi:[0,1]
	v_pk_add_f32 v[56:57], v[56:57], v[62:63]
	v_mov_b32_e32 v65, v54
	v_pk_add_f32 v[62:63], v[56:57], v[54:55] op_sel:[1,0] op_sel_hi:[0,1] neg_lo:[0,1] neg_hi:[0,1]
	v_mov_b32_e32 v64, v61
	v_mov_b32_e32 v60, v59
	v_mov_b32_e32 v61, v57
	v_pk_mov_b32 v[54:55], v[54:55], v[62:63] op_sel:[1,0]
	v_pk_add_f32 v[58:59], v[58:59], v[62:63] op_sel_hi:[1,0] neg_lo:[0,1] neg_hi:[0,1]
	v_pk_add_f32 v[54:55], v[60:61], v[54:55] neg_lo:[0,1] neg_hi:[0,1]
	v_mov_b32_e32 v58, v66
	v_pk_add_f32 v[54:55], v[64:65], v[54:55] neg_lo:[0,1] neg_hi:[0,1]
	v_mov_b32_e32 v67, v57
	v_pk_add_f32 v[58:59], v[58:59], v[54:55]
	s_nop 0
	v_pk_add_f32 v[60:61], v[58:59], v[58:59] op_sel:[0,1] op_sel_hi:[1,0]
	s_nop 0
	v_pk_add_f32 v[56:57], v[56:57], v[60:61] op_sel:[1,0] op_sel_hi:[0,1]
	v_mov_b32_e32 v59, v56
	v_mov_b32_e32 v55, v60
	v_pk_add_f32 v[60:61], v[58:59], v[66:67] neg_lo:[0,1] neg_hi:[0,1]
	s_nop 0
	v_sub_f32_e32 v41, v58, v60
	v_pk_add_f32 v[54:55], v[54:55], v[60:61] neg_lo:[0,1] neg_hi:[0,1]
	v_sub_f32_e32 v41, v66, v41
	v_add_f32_e32 v41, v54, v41
	v_add_f32_e32 v41, v41, v55
	v_add_f32_e32 v41, v56, v41
	v_cndmask_b32_e32 v41, v50, v41, vcc
	v_cmp_lt_f32_e64 vcc, |v34|, s37
	s_nop 1
	v_cndmask_b32_e32 v34, v41, v34, vcc
	v_sub_f32_e32 v34, v51, v34
	global_store_dword v[22:23], v34, off offset:128
	v_add_f32_e32 v34, v15, v24
	v_mul_f32_e64 v41, |v34|, s28
	v_fma_f32 v51, |v34|, s28, -v41
	v_rndne_f32_e32 v54, v41
; DI_ float log_sigmoid(float v) { return fminf(v, 0.f) - log1pf(expf(-fabsf(v))); }
; template <int NS, bool LN, bool WF32, bool WBF, int SKMODE>
; DI_ void row_pass(const float* Xin, float* Xout, bf16_t* XBo, const float* g, const float* b, const float* WsT, float* sk_out, const float* sk_bias, int row0, int nrows, int gw, int NGW, int lane) {
;     ...
;                 if ((lane & 7) == 0) sk_out[(size_t)row * NS + jo] = (SKMODE == 1) ? log_sigmoid(a[0] + sk_bias[jo]) : a[0];
	v_fma_f32 v51, |v34|, s29, v51
	v_sub_f32_e32 v41, v41, v54
	v_add_f32_e32 v41, v41, v51
	v_cvt_i32_f32_e32 v54, v54
	v_exp_f32_e32 v41, v41
	v_cmp_ngt_f32_e64 vcc, |v34|, s30
	v_min_f32_e32 v51, 0, v34
	v_ldexp_f32 v41, v41, v54
	v_cndmask_b32_e32 v41, 0, v41, vcc
	v_cmp_nlt_f32_e64 vcc, |v34|, s31
	s_nop 1
	v_cndmask_b32_e32 v34, v50, v41, vcc
	v_add_f32_e32 v41, 1.0, v34
	v_add_f32_e32 v56, -1.0, v41
	v_frexp_mant_f32_e32 v57, v41
	v_cvt_f64_f32_e32 v[54:55], v41
	v_sub_f32_e32 v58, v56, v41
	v_frexp_exp_i32_f64_e32 v54, v[54:55]
	v_cmp_gt_f32_e32 vcc, s35, v57
	v_sub_f32_e32 v56, v34, v56
	v_add_f32_e32 v55, 1.0, v58
	v_subbrev_co_u32_e32 v54, vcc, 0, v54, vcc
	v_add_f32_e32 v55, v56, v55
	v_sub_u32_e32 v56, 0, v54
	v_ldexp_f32 v41, v41, v56
	v_ldexp_f32 v55, v55, v56
	v_add_f32_e32 v56, -1.0, v41
	v_add_f32_e32 v58, 1.0, v41
	v_add_f32_e32 v57, 1.0, v56
	v_add_f32_e32 v59, -1.0, v58
	v_sub_f32_e32 v57, v41, v57
	v_sub_f32_e32 v41, v41, v59
	v_add_f32_e32 v41, v55, v41
	v_add_f32_e32 v59, v55, v57
	v_add_f32_e32 v55, v58, v41
	v_rcp_f32_e32 v62, v55
	v_add_f32_e32 v57, v56, v59
	v_sub_f32_e32 v58, v58, v55
	v_add_f32_e32 v41, v41, v58
	v_mul_f32_e32 v64, v57, v62
	v_mul_f32_e32 v58, v55, v64
	v_fma_f32 v60, v64, v55, -v58
	v_sub_f32_e32 v56, v56, v57
	v_fmac_f32_e32 v60, v64, v41
	v_add_f32_e32 v63, v59, v56
	v_add_f32_e32 v56, v58, v60
	v_sub_f32_e32 v59, v57, v56
	v_mov_b32_e32 v61, v56
	v_pk_add_f32 v[56:57], v[56:57], v[58:59] neg_lo:[0,1] neg_hi:[0,1]
	v_cvt_f32_i32_e32 v54, v54
	v_pk_add_f32 v[56:57], v[56:57], v[60:61] neg_lo:[0,1] neg_hi:[0,1]
	v_cmp_neq_f32_e32 vcc, s34, v34
	v_add_f32_e32 v57, v63, v57
	v_add_f32_e32 v56, v56, v57
	v_add_f32_e32 v57, v59, v56
	v_mul_f32_e32 v61, v62, v57
	v_mul_f32_e32 v58, v55, v61
	v_fma_f32 v60, v61, v55, -v58
	v_sub_f32_e32 v59, v59, v57
	v_fmac_f32_e32 v60, v61, v41
	v_add_f32_e32 v63, v56, v59
	v_add_f32_e32 v65, v64, v61
	v_add_f32_e32 v56, v58, v60
	v_sub_f32_e32 v55, v65, v64
	v_sub_f32_e32 v59, v57, v56
	v_sub_f32_e32 v41, v61, v55
	v_mov_b32_e32 v61, v56
	v_pk_add_f32 v[56:57], v[56:57], v[58:59] neg_lo:[0,1] neg_hi:[0,1]
	s_nop 0
	v_pk_add_f32 v[56:57], v[56:57], v[60:61] neg_lo:[0,1] neg_hi:[0,1]
	s_nop 0
	v_add_f32_e32 v55, v63, v57
	v_add_f32_e32 v55, v56, v55
	v_add_f32_e32 v55, v59, v55
	v_mul_f32_e32 v55, v62, v55
	v_add_f32_e32 v41, v41, v55
	v_add_f32_e32 v55, v65, v41
	v_mul_f32_e32 v56, v55, v55
	v_sub_f32_e32 v58, v55, v65
	v_fmamk_f32 v59, v56, 0x3e9b6dac, v49
	v_ldexp_f32 v57, v55, 1
	v_sub_f32_e32 v58, v41, v58
	v_mul_f32_e32 v55, v55, v56
	v_fmaak_f32 v41, v56, v59, 0x3f2aaada
	v_ldexp_f32 v61, v58, 1
	v_pk_mul_f32 v[58:59], v[54:55], v[40:41]
	s_nop 0
	v_fma_f32 v56, v54, s36, -v58
	v_fmac_f32_e32 v56, 0xb102e308, v54
	v_pk_add_f32 v[54:55], v[58:59], v[56:57]
	v_mov_b32_e32 v60, v58
	v_sub_f32_e32 v41, v55, v57
	v_sub_f32_e32 v41, v59, v41
	v_add_f32_e32 v61, v61, v41
	v_pk_add_f32 v[62:63], v[54:55], v[58:59] neg_lo:[0,1] neg_hi:[0,1]
	v_pk_add_f32 v[58:59], v[54:55], v[60:61]
	v_mov_b32_e32 v57, v54
	v_mov_b32_e32 v63, v59
	v_pk_add_f32 v[66:67], v[56:57], v[62:63] neg_lo:[0,1] neg_hi:[0,1]
	v_pk_add_f32 v[56:57], v[56:57], v[62:63]
	v_mov_b32_e32 v65, v54
	v_pk_add_f32 v[62:63], v[56:57], v[54:55] op_sel:[1,0] op_sel_hi:[0,1] neg_lo:[0,1] neg_hi:[0,1]
	v_mov_b32_e32 v64, v61
	v_mov_b32_e32 v60, v59
	v_mov_b32_e32 v61, v57
	v_pk_mov_b32 v[54:55], v[54:55], v[62:63] op_sel:[1,0]
	v_pk_add_f32 v[58:59], v[58:59], v[62:63] op_sel_hi:[1,0] neg_lo:[0,1] neg_hi:[0,1]
	v_pk_add_f32 v[54:55], v[60:61], v[54:55] neg_lo:[0,1] neg_hi:[0,1]
	v_mov_b32_e32 v58, v66
	v_pk_add_f32 v[54:55], v[64:65], v[54:55] neg_lo:[0,1] neg_hi:[0,1]
	v_mov_b32_e32 v67, v57
	v_pk_add_f32 v[58:59], v[58:59], v[54:55]
	s_nop 0
	v_pk_add_f32 v[60:61], v[58:59], v[58:59] op_sel:[0,1] op_sel_hi:[1,0]
	s_nop 0
	v_pk_add_f32 v[56:57], v[56:57], v[60:61] op_sel:[1,0] op_sel_hi:[0,1]
	v_mov_b32_e32 v59, v56
	v_mov_b32_e32 v55, v60
	v_pk_add_f32 v[60:61], v[58:59], v[66:67] neg_lo:[0,1] neg_hi:[0,1]
	s_nop 0
	v_sub_f32_e32 v41, v58, v60
	v_pk_add_f32 v[54:55], v[54:55], v[60:61] neg_lo:[0,1] neg_hi:[0,1]
	v_sub_f32_e32 v41, v66, v41
	v_add_f32_e32 v41, v54, v41
	v_add_f32_e32 v41, v41, v55
	v_add_f32_e32 v41, v56, v41
	v_cndmask_b32_e32 v41, v50, v41, vcc
	v_cmp_lt_f32_e64 vcc, |v34|, s37
	s_nop 1
	v_cndmask_b32_e32 v34, v41, v34, vcc
	v_sub_f32_e32 v34, v51, v34
	global_store_dword v[22:23], v34, off offset:192
